# L6 GEMM-out epilogue: batched residual/gate loads per row-block, 2-deep software pipelining with counted vmcnt (was 96 serialized load-wait-store round trips)
# speedup vs baseline: 1.0198x; 1.0198x over previous
.LBB0_1137:
	s_waitcnt vmcnt(9)
	ds_write_b128 v204, v[96:99]
	s_waitcnt vmcnt(8)
	ds_write_b128 v204, v[100:103] offset:4608
	s_waitcnt vmcnt(7)
	ds_write_b128 v204, v[104:107] offset:9216
	s_waitcnt vmcnt(6)
	ds_write_b128 v204, v[108:111] offset:13824
	s_waitcnt vmcnt(5)
	ds_write_b128 v204, v[112:115] offset:18432
	s_waitcnt vmcnt(4)
	ds_write_b128 v204, v[116:119] offset:23040
	s_waitcnt vmcnt(3)
	ds_write_b128 v204, v[120:123] offset:27648
	s_waitcnt vmcnt(2)
	ds_write_b128 v204, v[124:127] offset:32256
	s_waitcnt vmcnt(1)
	ds_write_b128 v204, v[128:131] offset:36864
	s_waitcnt vmcnt(0)
	ds_write_b128 v204, v[132:135] offset:41472
	s_waitcnt lgkmcnt(0)
	s_barrier
	ds_read_b128 v[96:99], v206
	ds_read_b128 v[100:103], v205 offset:27648
	ds_read_b128 v[120:123], v205 offset:27712
	ds_read_b128 v[104:107], v206 offset:64
	ds_read_b128 v[108:111], v205 offset:29952
	ds_read_b128 v[132:135], v205 offset:30016
	ds_read_b128 v[112:115], v205 offset:32256
	ds_read_b128 v[208:211], v205 offset:32320
	ds_read_b128 v[116:119], v205 offset:34560
	ds_read_b128 v[136:139], v205 offset:34624
	s_waitcnt lgkmcnt(8)
	v_mfma_f32_16x16x32_bf16 v[80:83], v[96:99], v[100:103], v[80:83]
	s_mov_b32 s6, 0xf600000
	s_waitcnt lgkmcnt(5)
	v_mfma_f32_16x16x32_bf16 v[72:75], v[96:99], v[108:111], v[72:75]
	s_waitcnt lgkmcnt(3)
	v_mfma_f32_16x16x32_bf16 v[60:63], v[96:99], v[112:115], v[60:63]
	s_waitcnt lgkmcnt(1)
	v_mfma_f32_16x16x32_bf16 v[56:59], v[96:99], v[116:119], v[56:59]
	ds_read_b128 v[96:99], v206 offset:2304
	ds_read_b128 v[124:127], v206 offset:2368
	s_waitcnt lgkmcnt(1)
	v_mfma_f32_16x16x32_bf16 v[52:55], v[96:99], v[100:103], v[52:55]
	v_mfma_f32_16x16x32_bf16 v[48:51], v[96:99], v[108:111], v[48:51]
	v_mfma_f32_16x16x32_bf16 v[36:39], v[96:99], v[112:115], v[36:39]
	v_mfma_f32_16x16x32_bf16 v[24:27], v[96:99], v[116:119], v[24:27]
	ds_read_b128 v[96:99], v206 offset:4608
	ds_read_b128 v[128:131], v206 offset:4672
	s_waitcnt lgkmcnt(1)
	v_mfma_f32_16x16x32_bf16 v[8:11], v[96:99], v[100:103], v[8:11]
	v_mfma_f32_16x16x32_bf16 v[0:3], v[96:99], v[108:111], v[0:3]
	v_mfma_f32_16x16x32_bf16 v[12:15], v[96:99], v[112:115], v[12:15]
	v_mfma_f32_16x16x32_bf16 v[20:23], v[96:99], v[116:119], v[20:23]
	ds_read_b128 v[96:99], v206 offset:6912
	ds_read_b128 v[212:215], v206 offset:6976
	s_waitcnt lgkmcnt(1)
	v_mfma_f32_16x16x32_bf16 v[4:7], v[96:99], v[100:103], v[4:7]
	v_mfma_f32_16x16x32_bf16 v[16:19], v[96:99], v[108:111], v[16:19]
	v_mfma_f32_16x16x32_bf16 v[32:35], v[96:99], v[112:115], v[32:35]
	v_mfma_f32_16x16x32_bf16 v[44:47], v[96:99], v[116:119], v[44:47]
	ds_read_b128 v[96:99], v206 offset:9216
	ds_read_b128 v[216:219], v206 offset:9280
	s_waitcnt lgkmcnt(1)
	v_mfma_f32_16x16x32_bf16 v[28:31], v[96:99], v[100:103], v[28:31]
	v_mfma_f32_16x16x32_bf16 v[40:43], v[96:99], v[108:111], v[40:43]
	v_mfma_f32_16x16x32_bf16 v[88:91], v[96:99], v[112:115], v[88:91]
	v_mfma_f32_16x16x32_bf16 v[84:87], v[96:99], v[116:119], v[84:87]
	ds_read_b128 v[96:99], v206 offset:11520
	ds_read_b128 v[140:143], v206 offset:11584
	s_waitcnt lgkmcnt(1)
	v_mfma_f32_16x16x32_bf16 v[76:79], v[96:99], v[100:103], v[76:79]
	v_mfma_f32_16x16x32_bf16 v[68:71], v[96:99], v[108:111], v[68:71]
	v_mfma_f32_16x16x32_bf16 v[64:67], v[96:99], v[112:115], v[64:67]
	v_mfma_f32_16x16x32_bf16 v[92:95], v[96:99], v[116:119], v[92:95]
	v_lshl_add_u64 v[96:97], v[162:163], 0, s[2:3]
	v_add_co_u32_e32 v100, vcc, s6, v96
	s_mov_b32 s6, 0xf610000
	s_nop 0
	v_addc_co_u32_e32 v101, vcc, 0, v97, vcc
	v_add_co_u32_e32 v102, vcc, s6, v96
	s_mov_b32 s6, 0xf620000
	s_nop 0
	v_addc_co_u32_e32 v103, vcc, 0, v97, vcc
	v_mfma_f32_16x16x32_bf16 v[80:83], v[104:107], v[120:123], v[80:83]
	v_lshl_add_u64 v[98:99], v[164:165], 0, s[2:3]
	s_add_u32 s2, s2, 0x80
	s_addc_u32 s3, s3, 0
	v_mfma_f32_16x16x32_bf16 v[72:75], v[104:107], v[132:135], v[72:75]
	s_cmpk_eq_i32 s2, 0x780
	v_mfma_f32_16x16x32_bf16 v[60:63], v[104:107], v[208:211], v[60:63]
	v_mfma_f32_16x16x32_bf16 v[56:59], v[104:107], v[136:139], v[56:59]
	v_add_co_u32_e32 v104, vcc, s6, v96
	s_mov_b32 s6, 0xf630000
	s_nop 0
	v_addc_co_u32_e32 v105, vcc, 0, v97, vcc
	v_add_co_u32_e32 v108, vcc, s6, v96
	s_mov_b32 s6, 0xf640000
	s_nop 0
	v_addc_co_u32_e32 v109, vcc, 0, v97, vcc
	v_add_co_u32_e32 v112, vcc, s6, v96
	s_mov_b32 s6, 0xf650000
	s_nop 0
	v_addc_co_u32_e32 v113, vcc, 0, v97, vcc
	v_add_co_u32_e32 v116, vcc, s6, v96
	s_mov_b32 s6, 0x11c80000
	s_nop 0
	v_addc_co_u32_e32 v117, vcc, 0, v97, vcc
	v_mfma_f32_16x16x32_bf16 v[52:55], v[124:127], v[120:123], v[52:55]
	v_mfma_f32_16x16x32_bf16 v[48:51], v[124:127], v[132:135], v[48:51]
	v_mfma_f32_16x16x32_bf16 v[36:39], v[124:127], v[208:211], v[36:39]
	v_mfma_f32_16x16x32_bf16 v[24:27], v[124:127], v[136:139], v[24:27]
	v_add_co_u32_e32 v124, vcc, s6, v98
	s_mov_b32 s6, 0x11c90000
	s_nop 0
	v_addc_co_u32_e32 v125, vcc, 0, v99, vcc
	v_add_co_u32_e32 v126, vcc, s6, v98
	s_mov_b32 s6, 0x11ca0000
	s_nop 0
	v_addc_co_u32_e32 v127, vcc, 0, v99, vcc
	v_mfma_f32_16x16x32_bf16 v[8:11], v[128:131], v[120:123], v[8:11]
	v_mfma_f32_16x16x32_bf16 v[0:3], v[128:131], v[132:135], v[0:3]
	v_mfma_f32_16x16x32_bf16 v[12:15], v[128:131], v[208:211], v[12:15]
	v_mfma_f32_16x16x32_bf16 v[20:23], v[128:131], v[136:139], v[20:23]
	v_add_co_u32_e32 v128, vcc, s6, v98
	s_mov_b32 s6, 0x11cb0000
	s_nop 0
	v_addc_co_u32_e32 v129, vcc, 0, v99, vcc
	v_mfma_f32_16x16x32_bf16 v[4:7], v[212:215], v[120:123], v[4:7]
	v_mfma_f32_16x16x32_bf16 v[16:19], v[212:215], v[132:135], v[16:19]
	v_mfma_f32_16x16x32_bf16 v[32:35], v[212:215], v[208:211], v[32:35]
	v_mfma_f32_16x16x32_bf16 v[44:47], v[212:215], v[136:139], v[44:47]
	v_add_co_u32_e32 v212, vcc, s6, v98
	v_mfma_f32_16x16x32_bf16 v[28:31], v[216:219], v[120:123], v[28:31]
	s_nop 0
	v_addc_co_u32_e32 v213, vcc, 0, v99, vcc
	global_load_dwordx4 v[96:99], v[100:101], off offset:128
	s_nop 0
	global_load_dwordx4 v[100:103], v[102:103], off offset:128
	s_nop 0
	global_load_dwordx4 v[104:107], v[104:105], off offset:128
	s_nop 0
	global_load_dwordx4 v[108:111], v[108:109], off offset:128
	s_nop 0
	global_load_dwordx4 v[112:115], v[112:113], off offset:128
	s_nop 0
	global_load_dwordx4 v[116:119], v[116:117], off offset:128
	s_waitcnt lgkmcnt(0)
	v_mfma_f32_16x16x32_bf16 v[76:79], v[140:143], v[120:123], v[76:79]
	global_load_dwordx4 v[120:123], v[124:125], off offset:128
	s_nop 0
	global_load_dwordx4 v[124:127], v[126:127], off offset:128
	s_nop 0
	global_load_dwordx4 v[128:131], v[128:129], off offset:128
	v_mfma_f32_16x16x32_bf16 v[40:43], v[216:219], v[132:135], v[40:43]
	v_mfma_f32_16x16x32_bf16 v[68:71], v[140:143], v[132:135], v[68:71]
	global_load_dwordx4 v[132:135], v[212:213], off offset:128
	s_barrier
	v_mfma_f32_16x16x32_bf16 v[88:91], v[216:219], v[208:211], v[88:91]
	v_mfma_f32_16x16x32_bf16 v[84:87], v[216:219], v[136:139], v[84:87]
	v_mfma_f32_16x16x32_bf16 v[64:67], v[140:143], v[208:211], v[64:67]
	v_mfma_f32_16x16x32_bf16 v[92:95], v[140:143], v[136:139], v[92:95]
	s_cbranch_scc0 .LBB0_1137
	s_waitcnt vmcnt(9)
	ds_write_b128 v204, v[96:99]
	s_waitcnt vmcnt(8)
	ds_write_b128 v204, v[100:103] offset:4608
	s_waitcnt vmcnt(7)
	ds_write_b128 v204, v[104:107] offset:9216
	s_waitcnt vmcnt(6)
	ds_write_b128 v204, v[108:111] offset:13824
	s_waitcnt vmcnt(5)
	ds_write_b128 v204, v[112:115] offset:18432
	s_waitcnt vmcnt(4)
	ds_write_b128 v204, v[116:119] offset:23040
	s_waitcnt vmcnt(3)
	ds_write_b128 v204, v[120:123] offset:27648
	s_waitcnt vmcnt(2)
	ds_write_b128 v204, v[124:127] offset:32256
	s_waitcnt vmcnt(1)
	ds_write_b128 v204, v[128:131] offset:36864
	s_waitcnt vmcnt(0)
	ds_write_b128 v204, v[132:135] offset:41472
	s_waitcnt lgkmcnt(0)
	s_barrier
	ds_read_b128 v[96:99], v205 offset:27648
	ds_read_b128 v[100:103], v205 offset:29952
	ds_read_b128 v[104:107], v205 offset:32256
	ds_read_b128 v[108:111], v205 offset:34560
	ds_read_b128 v[112:115], v206
	s_waitcnt lgkmcnt(0)
	v_mfma_f32_16x16x32_bf16 v[80:83], v[112:115], v[96:99], v[80:83]
	v_readlane_b32 s8, v251, 45
	s_movk_i32 s6, 0x1000
	v_readlane_b32 s9, v251, 46
	v_mfma_f32_16x16x32_bf16 v[72:75], v[112:115], v[100:103], v[72:75]
	v_readlane_b32 s10, v251, 47
	v_readlane_b32 s11, v251, 48
	v_mov_b32_e32 v161, v149
	v_mfma_f32_16x16x32_bf16 v[60:63], v[112:115], v[104:107], v[60:63]
	v_readlane_b32 s12, v251, 49
	v_readlane_b32 s14, v251, 51
	v_readlane_b32 s15, v251, 52
	v_mfma_f32_16x16x32_bf16 v[56:59], v[112:115], v[108:111], v[56:59]
	ds_read_b128 v[112:115], v206 offset:2304
	s_mov_b64 s[14:15], 0x12482000
	s_mov_b32 s12, 0x12482000
	s_waitcnt lgkmcnt(0)
	v_mfma_f32_16x16x32_bf16 v[52:55], v[112:115], v[96:99], v[52:55]
	s_movk_i32 s53, 0x1000
	v_readlane_b32 s13, v251, 50
	v_readlane_b32 s16, v251, 53
	v_mfma_f32_16x16x32_bf16 v[48:51], v[112:115], v[100:103], v[48:51]
	v_readlane_b32 s17, v251, 54
	v_readlane_b32 s18, v251, 55
	v_readlane_b32 s19, v251, 56
	v_mfma_f32_16x16x32_bf16 v[36:39], v[112:115], v[104:107], v[36:39]
	v_readlane_b32 s20, v251, 57
	v_readlane_b32 s21, v251, 58
	v_readlane_b32 s22, v251, 59
	v_mfma_f32_16x16x32_bf16 v[24:27], v[112:115], v[108:111], v[24:27]
	ds_read_b128 v[112:115], v206 offset:4608
	v_readlane_b32 s23, v251, 60
	s_waitcnt lgkmcnt(0)
	v_mfma_f32_16x16x32_bf16 v[8:11], v[112:115], v[96:99], v[8:11]
	v_mfma_f32_16x16x32_bf16 v[0:3], v[112:115], v[100:103], v[0:3]
	v_mfma_f32_16x16x32_bf16 v[12:15], v[112:115], v[104:107], v[12:15]
	v_mfma_f32_16x16x32_bf16 v[20:23], v[112:115], v[108:111], v[20:23]
	ds_read_b128 v[112:115], v206 offset:6912
	s_waitcnt lgkmcnt(0)
	v_mfma_f32_16x16x32_bf16 v[4:7], v[112:115], v[96:99], v[4:7]
	v_mfma_f32_16x16x32_bf16 v[16:19], v[112:115], v[100:103], v[16:19]
	v_mfma_f32_16x16x32_bf16 v[32:35], v[112:115], v[104:107], v[32:35]
	v_mfma_f32_16x16x32_bf16 v[112:115], v[112:115], v[108:111], v[44:47]
	s_nop 2
	ds_read_b128 v[44:47], v206 offset:9216
	s_waitcnt lgkmcnt(0)
	v_mfma_f32_16x16x32_bf16 v[116:119], v[44:47], v[100:103], v[40:43]
	s_nop 2
	ds_read_b128 v[40:43], v206 offset:11520
	v_mfma_f32_16x16x32_bf16 v[28:31], v[44:47], v[96:99], v[28:31]
	v_mfma_f32_16x16x32_bf16 v[120:123], v[44:47], v[104:107], v[88:91]
	v_mfma_f32_16x16x32_bf16 v[124:127], v[44:47], v[108:111], v[84:87]
	s_waitcnt lgkmcnt(0)
	v_mfma_f32_16x16x32_bf16 v[96:99], v[40:43], v[96:99], v[76:79]
	v_mfma_f32_16x16x32_bf16 v[100:103], v[40:43], v[100:103], v[68:71]
	v_mfma_f32_16x16x32_bf16 v[104:107], v[40:43], v[104:107], v[64:67]
	v_mfma_f32_16x16x32_bf16 v[108:111], v[40:43], v[108:111], v[92:95]
	ds_read_b128 v[128:131], v205 offset:27712
	ds_read_b128 v[132:135], v205 offset:30016
	ds_read_b128 v[136:139], v205 offset:32320
	ds_read_b128 v[140:143], v205 offset:34624
	ds_read_b128 v[40:43], v206 offset:64
	s_waitcnt lgkmcnt(0)
	v_mfma_f32_16x16x32_bf16 v[92:95], v[40:43], v[128:131], v[80:83]
	v_mfma_f32_16x16x32_bf16 v[88:91], v[40:43], v[132:135], v[72:75]
	v_mfma_f32_16x16x32_bf16 v[84:87], v[40:43], v[136:139], v[60:63]
	v_mfma_f32_16x16x32_bf16 v[80:83], v[40:43], v[140:143], v[56:59]
	ds_read_b128 v[40:43], v206 offset:2368
	s_waitcnt lgkmcnt(0)
	v_mfma_f32_16x16x32_bf16 v[64:67], v[40:43], v[140:143], v[24:27]
	s_nop 2
	ds_read_b128 v[24:27], v206 offset:4672
	s_waitcnt lgkmcnt(0)
	v_mfma_f32_16x16x32_bf16 v[56:59], v[24:27], v[132:135], v[0:3]
	s_nop 2
	ds_read_b128 v[0:3], v206 offset:6976
	v_mfma_f32_16x16x32_bf16 v[76:79], v[40:43], v[128:131], v[52:55]
	v_mfma_f32_16x16x32_bf16 v[72:75], v[40:43], v[132:135], v[48:51]
	v_mfma_f32_16x16x32_bf16 v[68:71], v[40:43], v[136:139], v[36:39]
	s_waitcnt lgkmcnt(0)
	v_mfma_f32_16x16x32_bf16 v[44:47], v[0:3], v[128:131], v[4:7]
	v_mfma_f32_16x16x32_bf16 v[40:43], v[0:3], v[132:135], v[16:19]
	v_mfma_f32_16x16x32_bf16 v[36:39], v[0:3], v[136:139], v[32:35]
	v_mfma_f32_16x16x32_bf16 v[32:35], v[0:3], v[140:143], v[112:115]
	ds_read_b128 v[0:3], v206 offset:9280
	v_mfma_f32_16x16x32_bf16 v[60:63], v[24:27], v[128:131], v[8:11]
	v_mfma_f32_16x16x32_bf16 v[52:55], v[24:27], v[136:139], v[12:15]
	v_mfma_f32_16x16x32_bf16 v[48:51], v[24:27], v[140:143], v[20:23]
	s_waitcnt lgkmcnt(0)
	v_mfma_f32_16x16x32_bf16 v[28:31], v[0:3], v[128:131], v[28:31]
	v_mfma_f32_16x16x32_bf16 v[24:27], v[0:3], v[132:135], v[116:119]
	v_mfma_f32_16x16x32_bf16 v[20:23], v[0:3], v[136:139], v[120:123]
	v_mfma_f32_16x16x32_bf16 v[16:19], v[0:3], v[140:143], v[124:127]
	ds_read_b128 v[0:3], v206 offset:11584
	s_waitcnt lgkmcnt(0)
	s_barrier
	v_mfma_f32_16x16x32_bf16 v[12:15], v[0:3], v[128:131], v[96:99]
	s_nop 2
	v_add_u32_e32 v98, s1, v166
	s_ashr_i32 s1, s0, 31
	v_add_u32_e32 v97, 0xfffff000, v98
	s_lshl_b64 s[0:1], s[0:1], 2
	v_or_b32_e32 v96, v98, v167
	v_lshrrev_b32_e32 v97, 12, v97
	v_mfma_f32_16x16x32_bf16 v[4:7], v[0:3], v[136:139], v[104:107]
	s_add_u32 s2, s82, s0
	v_add_u32_e32 v99, 1, v97
	v_ashrrev_i32_e32 v97, 31, v96
	v_add_u32_e32 v106, 0xfffff000, v96
	v_mov_b32_e32 v107, v149
	v_mfma_f32_16x16x32_bf16 v[8:11], v[0:3], v[132:135], v[100:103]
	s_addc_u32 s3, s83, s1
	v_lshlrev_b64 v[106:107], 12, v[106:107]
	v_cmp_gt_i32_e32 vcc, s6, v96
	v_lshlrev_b64 v[100:101], 12, v[96:97]
	v_lshl_add_u64 v[102:103], s[2:3], 0, v[100:101]
	v_lshl_add_u64 v[100:101], s[8:9], 0, v[100:101]
	v_lshl_add_u64 v[106:107], s[10:11], 0, v[106:107]
	v_cndmask_b32_e32 v101, v107, v101, vcc
	v_cndmask_b32_e32 v100, v106, v100, vcc
	v_cndmask_b32_e64 v97, v99, 0, vcc
	v_lshl_add_u64 v[100:101], v[100:101], 0, s[0:1]
	v_add_u32_e32 v97, s4, v97
	v_lshl_add_u64 v[104:105], v[102:103], 0, v[148:149]
	v_cndmask_b32_e64 v100, v102, v100, s[36:37]
	v_mul_lo_u32 v102, v97, s24
	v_cndmask_b32_e64 v101, v103, v101, s[36:37]
	v_ashrrev_i32_e32 v103, 31, v102
	v_lshl_add_u64 v[102:103], v[102:103], 2, s[82:83]
	v_lshl_add_u64 v[102:103], v[102:103], 0, s[0:1]
	v_lshl_add_u64 v[102:103], v[102:103], 0, v[148:149]
	v_lshl_add_u64 v[102:103], v[102:103], 0, v[160:161]
	v_lshl_add_u64 v[106:107], v[102:103], 0, s[14:15]
	v_lshl_add_u64 v[100:101], v[100:101], 0, v[148:149]
	v_add_co_u32_e32 v102, vcc, s12, v102
	v_lshl_add_u64 v[100:101], v[100:101], 0, v[160:161]
	s_nop 0
	v_addc_co_u32_e32 v103, vcc, 0, v103, vcc
	global_load_dword v112, v[100:101], off
	v_lshl_add_u64 v[104:105], v[104:105], 0, v[160:161]
	global_load_dword v116, v[102:103], off
	v_mfma_f32_16x16x32_bf16 v[0:3], v[0:3], v[140:143], v[108:111]
	s_add_i32 s5, s5, s92
	s_cmp_ge_i32 s5, s93
	global_load_dword v113, v[100:101], off offset:64
	global_load_dword v117, v[106:107], off offset:64
	global_load_dword v114, v[100:101], off offset:128
	global_load_dword v118, v[106:107], off offset:128
	global_load_dword v115, v[100:101], off offset:192
	global_load_dword v119, v[106:107], off offset:192
	v_mov_b32_e32 v120, v92
	v_mov_b32_e32 v121, v88
	v_mov_b32_e32 v122, v84
	v_mov_b32_e32 v123, v80
	v_mov_b64_e32 v[124:125], v[104:105]
	v_or_b32_e32 v100, 1, v96
	v_ashrrev_i32_e32 v101, 31, v100
	v_lshlrev_b64 v[102:103], 12, v[100:101]
	v_cmp_gt_i32_e32 vcc, s6, v100
	v_lshl_add_u64 v[100:101], s[8:9], 0, v[102:103]
	v_lshl_add_u64 v[104:105], s[2:3], 0, v[102:103]
	v_add_u32_e32 v102, 0xfffff001, v96
	v_mov_b32_e32 v103, v149
	v_lshlrev_b64 v[102:103], 12, v[102:103]
	v_cndmask_b32_e64 v80, v99, 0, vcc
	v_lshl_add_u64 v[102:103], s[10:11], 0, v[102:103]
	v_add_u32_e32 v80, s4, v80
	v_cndmask_b32_e32 v100, v102, v100, vcc
	v_mul_lo_u32 v102, v80, s24
	v_cndmask_b32_e32 v101, v103, v101, vcc
	v_ashrrev_i32_e32 v103, 31, v102
	v_lshl_add_u64 v[102:103], v[102:103], 2, s[82:83]
	v_lshl_add_u64 v[102:103], v[102:103], 0, s[0:1]
	v_lshl_add_u64 v[100:101], v[100:101], 0, s[0:1]
	v_lshl_add_u64 v[102:103], v[102:103], 0, v[148:149]
	v_cndmask_b32_e64 v101, v105, v101, s[36:37]
	v_cndmask_b32_e64 v100, v104, v100, s[36:37]
	v_lshl_add_u64 v[102:103], v[102:103], 0, v[160:161]
	v_lshl_add_u64 v[106:107], v[104:105], 0, v[148:149]
	v_lshl_add_u64 v[104:105], v[102:103], 0, s[14:15]
	v_lshl_add_u64 v[100:101], v[100:101], 0, v[148:149]
	v_add_co_u32_e32 v102, vcc, s12, v102
	v_lshl_add_u64 v[100:101], v[100:101], 0, v[160:161]
	s_nop 0
	v_addc_co_u32_e32 v103, vcc, 0, v103, vcc
	global_load_dword v126, v[100:101], off
	global_load_dword v130, v[102:103], off
	v_lshl_add_u64 v[106:107], v[106:107], 0, v[160:161]
	global_load_dword v127, v[100:101], off offset:64
	global_load_dword v131, v[104:105], off offset:64
	global_load_dword v128, v[100:101], off offset:128
	global_load_dword v132, v[104:105], off offset:128
	global_load_dword v129, v[100:101], off offset:192
	global_load_dword v133, v[104:105], off offset:192
	v_mov_b32_e32 v134, v93
	v_mov_b32_e32 v135, v89
	v_mov_b32_e32 v136, v85
	v_mov_b32_e32 v137, v81
	v_mov_b64_e32 v[138:139], v[106:107]
	s_waitcnt vmcnt(8)
	v_fmac_f32_e32 v112, v120, v116
	v_fmac_f32_e32 v113, v121, v117
	v_fmac_f32_e32 v114, v122, v118
	v_fmac_f32_e32 v115, v123, v119
	global_store_dword v[124:125], v112, off
	global_store_dword v[124:125], v113, off offset:64
	global_store_dword v[124:125], v114, off offset:128
	global_store_dword v[124:125], v115, off offset:192
	v_or_b32_e32 v80, 2, v96
	v_ashrrev_i32_e32 v81, 31, v80
	v_lshlrev_b64 v[84:85], 12, v[80:81]
	v_lshl_add_u64 v[88:89], s[2:3], 0, v[84:85]
	v_cmp_gt_i32_e32 vcc, s6, v80
	v_lshl_add_u64 v[80:81], s[8:9], 0, v[84:85]
	v_add_u32_e32 v84, 0xfffff002, v96
	v_mov_b32_e32 v85, v149
	v_lshlrev_b64 v[84:85], 12, v[84:85]
	v_lshl_add_u64 v[84:85], s[10:11], 0, v[84:85]
	v_cndmask_b32_e32 v80, v84, v80, vcc
	v_cndmask_b32_e64 v84, v99, 0, vcc
	v_add_u32_e32 v84, s4, v84
	v_mul_lo_u32 v84, v84, s24
	v_cndmask_b32_e32 v81, v85, v81, vcc
	v_ashrrev_i32_e32 v85, 31, v84
	v_lshl_add_u64 v[84:85], v[84:85], 2, s[82:83]
	v_lshl_add_u64 v[84:85], v[84:85], 0, s[0:1]
	v_lshl_add_u64 v[80:81], v[80:81], 0, s[0:1]
	v_lshl_add_u64 v[84:85], v[84:85], 0, v[148:149]
	v_cndmask_b32_e64 v81, v89, v81, s[36:37]
	v_cndmask_b32_e64 v80, v88, v80, s[36:37]
	v_lshl_add_u64 v[84:85], v[84:85], 0, v[160:161]
	v_lshl_add_u64 v[92:93], v[88:89], 0, v[148:149]
	v_lshl_add_u64 v[88:89], v[84:85], 0, s[14:15]
	v_lshl_add_u64 v[80:81], v[80:81], 0, v[148:149]
	v_add_co_u32_e32 v84, vcc, s12, v84
	v_lshl_add_u64 v[80:81], v[80:81], 0, v[160:161]
	s_nop 0
	v_addc_co_u32_e32 v85, vcc, 0, v85, vcc
	global_load_dword v112, v[80:81], off
	v_lshl_add_u64 v[92:93], v[92:93], 0, v[160:161]
	global_load_dword v116, v[84:85], off
	global_load_dword v113, v[80:81], off offset:64
	global_load_dword v117, v[88:89], off offset:64
	global_load_dword v114, v[80:81], off offset:128
	global_load_dword v118, v[88:89], off offset:128
	global_load_dword v115, v[80:81], off offset:192
	global_load_dword v119, v[88:89], off offset:192
	v_mov_b32_e32 v120, v94
	v_mov_b32_e32 v121, v90
	v_mov_b32_e32 v122, v86
	v_mov_b32_e32 v123, v82
	v_mov_b64_e32 v[124:125], v[92:93]
	s_waitcnt vmcnt(12)
	v_fmac_f32_e32 v126, v134, v130
	v_fmac_f32_e32 v127, v135, v131
	v_fmac_f32_e32 v128, v136, v132
	v_fmac_f32_e32 v129, v137, v133
	global_store_dword v[138:139], v126, off
	global_store_dword v[138:139], v127, off offset:64
	global_store_dword v[138:139], v128, off offset:128
	global_store_dword v[138:139], v129, off offset:192
	v_or_b32_e32 v80, 3, v96
	v_ashrrev_i32_e32 v81, 31, v80
	v_lshlrev_b64 v[84:85], 12, v[80:81]
	v_lshl_add_u64 v[88:89], s[2:3], 0, v[84:85]
	v_cmp_gt_i32_e32 vcc, s6, v80
	v_lshl_add_u64 v[80:81], s[8:9], 0, v[84:85]
	v_add_u32_e32 v84, 0xfffff003, v96
	v_mov_b32_e32 v85, v149
	v_lshlrev_b64 v[84:85], 12, v[84:85]
	v_cndmask_b32_e64 v82, v99, 0, vcc
	v_lshl_add_u64 v[84:85], s[10:11], 0, v[84:85]
	v_add_u32_e32 v82, s4, v82
	v_cndmask_b32_e32 v80, v84, v80, vcc
	v_mul_lo_u32 v84, v82, s24
	v_cndmask_b32_e32 v81, v85, v81, vcc
	v_ashrrev_i32_e32 v85, 31, v84
	v_lshl_add_u64 v[84:85], v[84:85], 2, s[82:83]
	v_lshl_add_u64 v[84:85], v[84:85], 0, s[0:1]
	v_lshl_add_u64 v[80:81], v[80:81], 0, s[0:1]
	v_lshl_add_u64 v[84:85], v[84:85], 0, v[148:149]
	v_cndmask_b32_e64 v81, v89, v81, s[36:37]
	v_cndmask_b32_e64 v80, v88, v80, s[36:37]
	v_lshl_add_u64 v[84:85], v[84:85], 0, v[160:161]
	v_lshl_add_u64 v[92:93], v[88:89], 0, v[148:149]
	v_lshl_add_u64 v[88:89], v[84:85], 0, s[14:15]
	v_lshl_add_u64 v[80:81], v[80:81], 0, v[148:149]
	v_add_co_u32_e32 v84, vcc, s12, v84
	v_lshl_add_u64 v[80:81], v[80:81], 0, v[160:161]
	s_nop 0
	v_addc_co_u32_e32 v85, vcc, 0, v85, vcc
	global_load_dword v126, v[80:81], off
	v_lshl_add_u64 v[92:93], v[92:93], 0, v[160:161]
	global_load_dword v130, v[84:85], off
	global_load_dword v127, v[80:81], off offset:64
	global_load_dword v131, v[88:89], off offset:64
	global_load_dword v128, v[80:81], off offset:128
	global_load_dword v132, v[88:89], off offset:128
	global_load_dword v129, v[80:81], off offset:192
	global_load_dword v133, v[88:89], off offset:192
	v_mov_b32_e32 v134, v95
	v_mov_b32_e32 v135, v91
	v_mov_b32_e32 v136, v87
	v_mov_b32_e32 v137, v83
	v_mov_b64_e32 v[138:139], v[92:93]
	s_waitcnt vmcnt(12)
	v_fmac_f32_e32 v112, v120, v116
	v_fmac_f32_e32 v113, v121, v117
	v_fmac_f32_e32 v114, v122, v118
	v_fmac_f32_e32 v115, v123, v119
	global_store_dword v[124:125], v112, off
	global_store_dword v[124:125], v113, off offset:64
	global_store_dword v[124:125], v114, off offset:128
	global_store_dword v[124:125], v115, off offset:192
	v_or_b32_e32 v84, 16, v96
	v_ashrrev_i32_e32 v85, 31, v84
	v_lshlrev_b64 v[86:87], 12, v[84:85]
	v_lshl_add_u64 v[88:89], s[2:3], 0, v[86:87]
	v_cmp_gt_i32_e32 vcc, s6, v84
	v_lshl_add_u64 v[84:85], s[8:9], 0, v[86:87]
	v_add_u32_e32 v86, 0xfffff010, v96
	v_mov_b32_e32 v87, v149
	v_lshlrev_b64 v[86:87], 12, v[86:87]
	v_lshl_add_u64 v[86:87], s[10:11], 0, v[86:87]
	v_cndmask_b32_e32 v84, v86, v84, vcc
	v_cndmask_b32_e32 v85, v87, v85, vcc
	v_lshl_add_u64 v[84:85], v[84:85], 0, s[0:1]
	v_cndmask_b32_e64 v85, v89, v85, s[36:37]
	v_cndmask_b32_e64 v84, v88, v84, s[36:37]
	v_lshl_add_u64 v[84:85], v[84:85], 0, v[148:149]
	v_lshl_add_u64 v[84:85], v[84:85], 0, v[160:161]
	v_add_u32_e32 v80, 0xfffff010, v98
	v_lshrrev_b32_e32 v80, 12, v80
	v_add_u32_e32 v82, 1, v80
	v_cndmask_b32_e64 v83, v82, 0, vcc
	v_add_u32_e32 v83, s4, v83
	v_mul_lo_u32 v86, v83, s24
	v_ashrrev_i32_e32 v87, 31, v86
	v_lshl_add_u64 v[86:87], v[86:87], 2, s[82:83]
	v_lshl_add_u64 v[86:87], v[86:87], 0, s[0:1]
	v_lshl_add_u64 v[86:87], v[86:87], 0, v[148:149]
	v_lshl_add_u64 v[86:87], v[86:87], 0, v[160:161]
	v_lshl_add_u64 v[80:81], v[88:89], 0, v[148:149]
	v_lshl_add_u64 v[88:89], v[86:87], 0, s[14:15]
	v_add_co_u32_e32 v86, vcc, s12, v86
	global_load_dword v112, v[84:85], off
	s_nop 0
	v_addc_co_u32_e32 v87, vcc, 0, v87, vcc
	global_load_dword v116, v[86:87], off
	v_lshl_add_u64 v[80:81], v[80:81], 0, v[160:161]
	global_load_dword v113, v[84:85], off offset:64
	global_load_dword v117, v[88:89], off offset:64
	global_load_dword v114, v[84:85], off offset:128
	global_load_dword v118, v[88:89], off offset:128
	global_load_dword v115, v[84:85], off offset:192
	global_load_dword v119, v[88:89], off offset:192
	v_mov_b32_e32 v120, v76
	v_mov_b32_e32 v121, v72
	v_mov_b32_e32 v122, v68
	v_mov_b32_e32 v123, v64
	v_mov_b64_e32 v[124:125], v[80:81]
	s_waitcnt vmcnt(12)
	v_fmac_f32_e32 v126, v134, v130
	v_fmac_f32_e32 v127, v135, v131
	v_fmac_f32_e32 v128, v136, v132
	v_fmac_f32_e32 v129, v137, v133
	global_store_dword v[138:139], v126, off
	global_store_dword v[138:139], v127, off offset:64
	global_store_dword v[138:139], v128, off offset:128
	global_store_dword v[138:139], v129, off offset:192
	v_or_b32_e32 v80, 17, v96
	v_ashrrev_i32_e32 v81, 31, v80
	v_lshlrev_b64 v[84:85], 12, v[80:81]
	v_lshl_add_u64 v[86:87], s[2:3], 0, v[84:85]
	v_cmp_gt_i32_e32 vcc, s6, v80
	v_lshl_add_u64 v[80:81], s[8:9], 0, v[84:85]
	v_add_u32_e32 v84, 0xfffff011, v96
	v_mov_b32_e32 v85, v149
	v_lshlrev_b64 v[84:85], 12, v[84:85]
	v_cndmask_b32_e64 v64, v82, 0, vcc
	v_lshl_add_u64 v[84:85], s[10:11], 0, v[84:85]
	v_add_u32_e32 v64, s4, v64
	v_cndmask_b32_e32 v80, v84, v80, vcc
	v_mul_lo_u32 v84, v64, s24
	v_cndmask_b32_e32 v81, v85, v81, vcc
	v_ashrrev_i32_e32 v85, 31, v84
	v_lshl_add_u64 v[84:85], v[84:85], 2, s[82:83]
	v_lshl_add_u64 v[84:85], v[84:85], 0, s[0:1]
	v_lshl_add_u64 v[80:81], v[80:81], 0, s[0:1]
	v_lshl_add_u64 v[84:85], v[84:85], 0, v[148:149]
	v_cndmask_b32_e64 v81, v87, v81, s[36:37]
	v_cndmask_b32_e64 v80, v86, v80, s[36:37]
	v_lshl_add_u64 v[84:85], v[84:85], 0, v[160:161]
	v_lshl_add_u64 v[88:89], v[86:87], 0, v[148:149]
	v_lshl_add_u64 v[86:87], v[84:85], 0, s[14:15]
	v_lshl_add_u64 v[80:81], v[80:81], 0, v[148:149]
	v_add_co_u32_e32 v84, vcc, s12, v84
	v_lshl_add_u64 v[80:81], v[80:81], 0, v[160:161]
	s_nop 0
	v_addc_co_u32_e32 v85, vcc, 0, v85, vcc
	global_load_dword v126, v[80:81], off
	global_load_dword v130, v[84:85], off
	v_lshl_add_u64 v[88:89], v[88:89], 0, v[160:161]
	global_load_dword v127, v[80:81], off offset:64
	global_load_dword v131, v[86:87], off offset:64
	global_load_dword v128, v[80:81], off offset:128
	global_load_dword v132, v[86:87], off offset:128
	global_load_dword v129, v[80:81], off offset:192
	global_load_dword v133, v[86:87], off offset:192
	v_mov_b32_e32 v134, v77
	v_mov_b32_e32 v135, v73
	v_mov_b32_e32 v136, v69
	v_mov_b32_e32 v137, v65
	v_mov_b64_e32 v[138:139], v[88:89]
	s_waitcnt vmcnt(12)
	v_fmac_f32_e32 v112, v120, v116
	v_fmac_f32_e32 v113, v121, v117
	v_fmac_f32_e32 v114, v122, v118
	v_fmac_f32_e32 v115, v123, v119
	global_store_dword v[124:125], v112, off
	global_store_dword v[124:125], v113, off offset:64
	global_store_dword v[124:125], v114, off offset:128
	global_store_dword v[124:125], v115, off offset:192
	v_or_b32_e32 v64, 18, v96
	v_ashrrev_i32_e32 v65, 31, v64
	v_lshlrev_b64 v[68:69], 12, v[64:65]
	v_lshl_add_u64 v[72:73], s[2:3], 0, v[68:69]
	v_cmp_gt_i32_e32 vcc, s6, v64
	v_lshl_add_u64 v[64:65], s[8:9], 0, v[68:69]
	v_add_u32_e32 v68, 0xfffff012, v96
	v_mov_b32_e32 v69, v149
	v_lshlrev_b64 v[68:69], 12, v[68:69]
	v_lshl_add_u64 v[68:69], s[10:11], 0, v[68:69]
	v_cndmask_b32_e32 v64, v68, v64, vcc
	v_cndmask_b32_e64 v68, v82, 0, vcc
	v_add_u32_e32 v68, s4, v68
	v_mul_lo_u32 v68, v68, s24
	v_cndmask_b32_e32 v65, v69, v65, vcc
	v_ashrrev_i32_e32 v69, 31, v68
	v_lshl_add_u64 v[68:69], v[68:69], 2, s[82:83]
	v_lshl_add_u64 v[68:69], v[68:69], 0, s[0:1]
	v_lshl_add_u64 v[64:65], v[64:65], 0, s[0:1]
	v_lshl_add_u64 v[68:69], v[68:69], 0, v[148:149]
	v_cndmask_b32_e64 v65, v73, v65, s[36:37]
	v_cndmask_b32_e64 v64, v72, v64, s[36:37]
	v_lshl_add_u64 v[68:69], v[68:69], 0, v[160:161]
	v_lshl_add_u64 v[76:77], v[72:73], 0, v[148:149]
	v_lshl_add_u64 v[72:73], v[68:69], 0, s[14:15]
	v_lshl_add_u64 v[64:65], v[64:65], 0, v[148:149]
	v_add_co_u32_e32 v68, vcc, s12, v68
	v_lshl_add_u64 v[64:65], v[64:65], 0, v[160:161]
	s_nop 0
	v_addc_co_u32_e32 v69, vcc, 0, v69, vcc
	global_load_dword v112, v[64:65], off
	v_lshl_add_u64 v[76:77], v[76:77], 0, v[160:161]
	global_load_dword v116, v[68:69], off
	global_load_dword v113, v[64:65], off offset:64
	global_load_dword v117, v[72:73], off offset:64
	global_load_dword v114, v[64:65], off offset:128
	global_load_dword v118, v[72:73], off offset:128
	global_load_dword v115, v[64:65], off offset:192
	global_load_dword v119, v[72:73], off offset:192
	v_mov_b32_e32 v120, v78
	v_mov_b32_e32 v121, v74
	v_mov_b32_e32 v122, v70
	v_mov_b32_e32 v123, v66
	v_mov_b64_e32 v[124:125], v[76:77]
	s_waitcnt vmcnt(12)
	v_fmac_f32_e32 v126, v134, v130
	v_fmac_f32_e32 v127, v135, v131
	v_fmac_f32_e32 v128, v136, v132
	v_fmac_f32_e32 v129, v137, v133
	global_store_dword v[138:139], v126, off
	global_store_dword v[138:139], v127, off offset:64
	global_store_dword v[138:139], v128, off offset:128
	global_store_dword v[138:139], v129, off offset:192
	v_or_b32_e32 v64, 19, v96
	v_ashrrev_i32_e32 v65, 31, v64
	v_lshlrev_b64 v[68:69], 12, v[64:65]
	v_lshl_add_u64 v[72:73], s[2:3], 0, v[68:69]
	v_cmp_gt_i32_e32 vcc, s6, v64
	v_lshl_add_u64 v[64:65], s[8:9], 0, v[68:69]
	v_add_u32_e32 v68, 0xfffff013, v96
	v_mov_b32_e32 v69, v149
	v_lshlrev_b64 v[68:69], 12, v[68:69]
	v_cndmask_b32_e64 v66, v82, 0, vcc
	v_lshl_add_u64 v[68:69], s[10:11], 0, v[68:69]
	v_add_u32_e32 v66, s4, v66
	v_cndmask_b32_e32 v64, v68, v64, vcc
	v_mul_lo_u32 v68, v66, s24
	v_cndmask_b32_e32 v65, v69, v65, vcc
	v_ashrrev_i32_e32 v69, 31, v68
	v_lshl_add_u64 v[68:69], v[68:69], 2, s[82:83]
	v_lshl_add_u64 v[68:69], v[68:69], 0, s[0:1]
	v_lshl_add_u64 v[64:65], v[64:65], 0, s[0:1]
	v_lshl_add_u64 v[68:69], v[68:69], 0, v[148:149]
	v_cndmask_b32_e64 v65, v73, v65, s[36:37]
	v_cndmask_b32_e64 v64, v72, v64, s[36:37]
	v_lshl_add_u64 v[68:69], v[68:69], 0, v[160:161]
	v_lshl_add_u64 v[76:77], v[72:73], 0, v[148:149]
	v_lshl_add_u64 v[72:73], v[68:69], 0, s[14:15]
	v_lshl_add_u64 v[64:65], v[64:65], 0, v[148:149]
	v_add_co_u32_e32 v68, vcc, s12, v68
	v_lshl_add_u64 v[64:65], v[64:65], 0, v[160:161]
	s_nop 0
	v_addc_co_u32_e32 v69, vcc, 0, v69, vcc
	global_load_dword v126, v[64:65], off
	v_lshl_add_u64 v[76:77], v[76:77], 0, v[160:161]
	global_load_dword v130, v[68:69], off
	global_load_dword v127, v[64:65], off offset:64
	global_load_dword v131, v[72:73], off offset:64
	global_load_dword v128, v[64:65], off offset:128
	global_load_dword v132, v[72:73], off offset:128
	global_load_dword v129, v[64:65], off offset:192
	global_load_dword v133, v[72:73], off offset:192
	v_mov_b32_e32 v134, v79
	v_mov_b32_e32 v135, v75
	v_mov_b32_e32 v136, v71
	v_mov_b32_e32 v137, v67
	v_mov_b64_e32 v[138:139], v[76:77]
	s_waitcnt vmcnt(12)
	v_fmac_f32_e32 v112, v120, v116
	v_fmac_f32_e32 v113, v121, v117
	v_fmac_f32_e32 v114, v122, v118
	v_fmac_f32_e32 v115, v123, v119
	global_store_dword v[124:125], v112, off
	global_store_dword v[124:125], v113, off offset:64
	global_store_dword v[124:125], v114, off offset:128
	global_store_dword v[124:125], v115, off offset:192
	v_mov_b32_e32 v75, v149
	v_add_u32_e32 v65, 0xfffff020, v98
	v_add_u32_e32 v64, v98, v168
	v_lshrrev_b32_e32 v65, 12, v65
	v_add_u32_e32 v68, 1, v65
	v_ashrrev_i32_e32 v65, 31, v64
	v_add_u32_e32 v74, 0xfffff000, v64
	v_lshlrev_b64 v[70:71], 12, v[64:65]
	v_lshlrev_b64 v[74:75], 12, v[74:75]
	v_lshl_add_u64 v[72:73], s[2:3], 0, v[70:71]
	v_cmp_gt_i32_e32 vcc, s6, v64
	v_lshl_add_u64 v[70:71], s[8:9], 0, v[70:71]
	v_lshl_add_u64 v[74:75], s[10:11], 0, v[74:75]
	v_cndmask_b32_e32 v71, v75, v71, vcc
	v_cndmask_b32_e32 v70, v74, v70, vcc
	v_cndmask_b32_e64 v65, v68, 0, vcc
	v_lshl_add_u64 v[70:71], v[70:71], 0, s[0:1]
	v_add_u32_e32 v65, s4, v65
	v_lshl_add_u64 v[66:67], v[72:73], 0, v[148:149]
	v_cndmask_b32_e64 v70, v72, v70, s[36:37]
	v_mul_lo_u32 v72, v65, s24
	v_cndmask_b32_e64 v71, v73, v71, s[36:37]
	v_ashrrev_i32_e32 v73, 31, v72
	v_lshl_add_u64 v[72:73], v[72:73], 2, s[82:83]
	v_lshl_add_u64 v[72:73], v[72:73], 0, s[0:1]
	v_lshl_add_u64 v[72:73], v[72:73], 0, v[148:149]
	v_lshl_add_u64 v[72:73], v[72:73], 0, v[160:161]
	v_lshl_add_u64 v[74:75], v[72:73], 0, s[14:15]
	v_lshl_add_u64 v[70:71], v[70:71], 0, v[148:149]
	v_add_co_u32_e32 v72, vcc, s12, v72
	v_lshl_add_u64 v[70:71], v[70:71], 0, v[160:161]
	s_nop 0
	v_addc_co_u32_e32 v73, vcc, 0, v73, vcc
	global_load_dword v112, v[70:71], off
	global_load_dword v116, v[72:73], off
	v_lshl_add_u64 v[66:67], v[66:67], 0, v[160:161]
	global_load_dword v113, v[70:71], off offset:64
	global_load_dword v117, v[74:75], off offset:64
	global_load_dword v114, v[70:71], off offset:128
	global_load_dword v118, v[74:75], off offset:128
	global_load_dword v115, v[70:71], off offset:192
	global_load_dword v119, v[74:75], off offset:192
	v_mov_b32_e32 v120, v60
	v_mov_b32_e32 v121, v56
	v_mov_b32_e32 v122, v52
	v_mov_b32_e32 v123, v48
	v_mov_b64_e32 v[124:125], v[66:67]
	s_waitcnt vmcnt(12)
	v_fmac_f32_e32 v126, v134, v130
	v_fmac_f32_e32 v127, v135, v131
	v_fmac_f32_e32 v128, v136, v132
	v_fmac_f32_e32 v129, v137, v133
	global_store_dword v[138:139], v126, off
	global_store_dword v[138:139], v127, off offset:64
	global_store_dword v[138:139], v128, off offset:128
	global_store_dword v[138:139], v129, off offset:192
	v_or_b32_e32 v66, 1, v64
	v_ashrrev_i32_e32 v67, 31, v66
	v_lshlrev_b64 v[70:71], 12, v[66:67]
	v_lshl_add_u64 v[72:73], s[2:3], 0, v[70:71]
	v_cmp_gt_i32_e32 vcc, s6, v66
	v_lshl_add_u64 v[66:67], s[8:9], 0, v[70:71]
	v_add_u32_e32 v70, 0xfffff001, v64
	v_mov_b32_e32 v71, v149
	v_lshlrev_b64 v[70:71], 12, v[70:71]
	v_cndmask_b32_e64 v48, v68, 0, vcc
	v_lshl_add_u64 v[70:71], s[10:11], 0, v[70:71]
	v_add_u32_e32 v48, s4, v48
	v_cndmask_b32_e32 v66, v70, v66, vcc
	v_mul_lo_u32 v70, v48, s24
	v_cndmask_b32_e32 v67, v71, v67, vcc
	v_ashrrev_i32_e32 v71, 31, v70
	v_lshl_add_u64 v[70:71], v[70:71], 2, s[82:83]
	v_lshl_add_u64 v[70:71], v[70:71], 0, s[0:1]
	v_lshl_add_u64 v[66:67], v[66:67], 0, s[0:1]
	v_lshl_add_u64 v[70:71], v[70:71], 0, v[148:149]
	v_cndmask_b32_e64 v67, v73, v67, s[36:37]
	v_cndmask_b32_e64 v66, v72, v66, s[36:37]
	v_lshl_add_u64 v[70:71], v[70:71], 0, v[160:161]
	v_lshl_add_u64 v[74:75], v[72:73], 0, v[148:149]
	v_lshl_add_u64 v[72:73], v[70:71], 0, s[14:15]
	v_lshl_add_u64 v[66:67], v[66:67], 0, v[148:149]
	v_add_co_u32_e32 v70, vcc, s12, v70
	v_lshl_add_u64 v[66:67], v[66:67], 0, v[160:161]
	s_nop 0
	v_addc_co_u32_e32 v71, vcc, 0, v71, vcc
	global_load_dword v126, v[66:67], off
	global_load_dword v130, v[70:71], off
	v_lshl_add_u64 v[74:75], v[74:75], 0, v[160:161]
	global_load_dword v127, v[66:67], off offset:64
	global_load_dword v131, v[72:73], off offset:64
	global_load_dword v128, v[66:67], off offset:128
	global_load_dword v132, v[72:73], off offset:128
	global_load_dword v129, v[66:67], off offset:192
	global_load_dword v133, v[72:73], off offset:192
	v_mov_b32_e32 v134, v61
	v_mov_b32_e32 v135, v57
	v_mov_b32_e32 v136, v53
	v_mov_b32_e32 v137, v49
	v_mov_b64_e32 v[138:139], v[74:75]
	s_waitcnt vmcnt(12)
	v_fmac_f32_e32 v112, v120, v116
	v_fmac_f32_e32 v113, v121, v117
	v_fmac_f32_e32 v114, v122, v118
	v_fmac_f32_e32 v115, v123, v119
	global_store_dword v[124:125], v112, off
	global_store_dword v[124:125], v113, off offset:64
	global_store_dword v[124:125], v114, off offset:128
	global_store_dword v[124:125], v115, off offset:192
	v_or_b32_e32 v48, 2, v64
	v_ashrrev_i32_e32 v49, 31, v48
	v_lshlrev_b64 v[52:53], 12, v[48:49]
	v_lshl_add_u64 v[56:57], s[2:3], 0, v[52:53]
	v_cmp_gt_i32_e32 vcc, s6, v48
	v_lshl_add_u64 v[48:49], s[8:9], 0, v[52:53]
	v_add_u32_e32 v52, 0xfffff002, v64
	v_mov_b32_e32 v53, v149
	v_lshlrev_b64 v[52:53], 12, v[52:53]
	v_lshl_add_u64 v[52:53], s[10:11], 0, v[52:53]
	v_cndmask_b32_e32 v48, v52, v48, vcc
	v_cndmask_b32_e64 v52, v68, 0, vcc
	v_add_u32_e32 v52, s4, v52
	v_mul_lo_u32 v52, v52, s24
	v_cndmask_b32_e32 v49, v53, v49, vcc
	v_ashrrev_i32_e32 v53, 31, v52
	v_lshl_add_u64 v[52:53], v[52:53], 2, s[82:83]
	v_lshl_add_u64 v[52:53], v[52:53], 0, s[0:1]
	v_lshl_add_u64 v[48:49], v[48:49], 0, s[0:1]
	v_lshl_add_u64 v[52:53], v[52:53], 0, v[148:149]
	v_cndmask_b32_e64 v49, v57, v49, s[36:37]
	v_cndmask_b32_e64 v48, v56, v48, s[36:37]
	v_lshl_add_u64 v[52:53], v[52:53], 0, v[160:161]
	v_lshl_add_u64 v[60:61], v[56:57], 0, v[148:149]
	v_lshl_add_u64 v[56:57], v[52:53], 0, s[14:15]
	v_lshl_add_u64 v[48:49], v[48:49], 0, v[148:149]
	v_add_co_u32_e32 v52, vcc, s12, v52
	v_lshl_add_u64 v[48:49], v[48:49], 0, v[160:161]
	s_nop 0
	v_addc_co_u32_e32 v53, vcc, 0, v53, vcc
	global_load_dword v112, v[48:49], off
	v_lshl_add_u64 v[60:61], v[60:61], 0, v[160:161]
	global_load_dword v116, v[52:53], off
	global_load_dword v113, v[48:49], off offset:64
	global_load_dword v117, v[56:57], off offset:64
	global_load_dword v114, v[48:49], off offset:128
	global_load_dword v118, v[56:57], off offset:128
	global_load_dword v115, v[48:49], off offset:192
	global_load_dword v119, v[56:57], off offset:192
	v_mov_b32_e32 v120, v62
	v_mov_b32_e32 v121, v58
	v_mov_b32_e32 v122, v54
	v_mov_b32_e32 v123, v50
	v_mov_b64_e32 v[124:125], v[60:61]
	s_waitcnt vmcnt(12)
	v_fmac_f32_e32 v126, v134, v130
	v_fmac_f32_e32 v127, v135, v131
	v_fmac_f32_e32 v128, v136, v132
	v_fmac_f32_e32 v129, v137, v133
	global_store_dword v[138:139], v126, off
	global_store_dword v[138:139], v127, off offset:64
	global_store_dword v[138:139], v128, off offset:128
	global_store_dword v[138:139], v129, off offset:192
	v_or_b32_e32 v48, 3, v64
	v_ashrrev_i32_e32 v49, 31, v48
	v_lshlrev_b64 v[52:53], 12, v[48:49]
	v_lshl_add_u64 v[56:57], s[2:3], 0, v[52:53]
	v_cmp_gt_i32_e32 vcc, s6, v48
	v_lshl_add_u64 v[48:49], s[8:9], 0, v[52:53]
	v_add_u32_e32 v52, 0xfffff003, v64
	v_mov_b32_e32 v53, v149
	v_lshlrev_b64 v[52:53], 12, v[52:53]
	v_cndmask_b32_e64 v50, v68, 0, vcc
	v_lshl_add_u64 v[52:53], s[10:11], 0, v[52:53]
	v_add_u32_e32 v50, s4, v50
	v_cndmask_b32_e32 v48, v52, v48, vcc
	v_mul_lo_u32 v52, v50, s24
	v_cndmask_b32_e32 v49, v53, v49, vcc
	v_ashrrev_i32_e32 v53, 31, v52
	v_lshl_add_u64 v[52:53], v[52:53], 2, s[82:83]
	v_lshl_add_u64 v[52:53], v[52:53], 0, s[0:1]
	v_lshl_add_u64 v[48:49], v[48:49], 0, s[0:1]
	v_lshl_add_u64 v[52:53], v[52:53], 0, v[148:149]
	v_cndmask_b32_e64 v49, v57, v49, s[36:37]
	v_cndmask_b32_e64 v48, v56, v48, s[36:37]
	v_lshl_add_u64 v[52:53], v[52:53], 0, v[160:161]
	v_lshl_add_u64 v[60:61], v[56:57], 0, v[148:149]
	v_lshl_add_u64 v[56:57], v[52:53], 0, s[14:15]
	v_lshl_add_u64 v[48:49], v[48:49], 0, v[148:149]
	v_add_co_u32_e32 v52, vcc, s12, v52
	v_lshl_add_u64 v[48:49], v[48:49], 0, v[160:161]
	s_nop 0
	v_addc_co_u32_e32 v53, vcc, 0, v53, vcc
	global_load_dword v126, v[48:49], off
	v_lshl_add_u64 v[60:61], v[60:61], 0, v[160:161]
	global_load_dword v130, v[52:53], off
	global_load_dword v127, v[48:49], off offset:64
	global_load_dword v131, v[56:57], off offset:64
	global_load_dword v128, v[48:49], off offset:128
	global_load_dword v132, v[56:57], off offset:128
	global_load_dword v129, v[48:49], off offset:192
	global_load_dword v133, v[56:57], off offset:192
	v_mov_b32_e32 v134, v63
	v_mov_b32_e32 v135, v59
	v_mov_b32_e32 v136, v55
	v_mov_b32_e32 v137, v51
	v_mov_b64_e32 v[138:139], v[60:61]
	s_waitcnt vmcnt(12)
	v_fmac_f32_e32 v112, v120, v116
	v_fmac_f32_e32 v113, v121, v117
	v_fmac_f32_e32 v114, v122, v118
	v_fmac_f32_e32 v115, v123, v119
	global_store_dword v[124:125], v112, off
	global_store_dword v[124:125], v113, off offset:64
	global_store_dword v[124:125], v114, off offset:128
	global_store_dword v[124:125], v115, off offset:192
	v_mov_b32_e32 v59, v149
	v_add_u32_e32 v49, 0xfffff030, v98
	v_add_u32_e32 v48, v98, v169
	v_lshrrev_b32_e32 v49, 12, v49
	v_add_u32_e32 v52, 1, v49
	v_ashrrev_i32_e32 v49, 31, v48
	v_add_u32_e32 v58, 0xfffff000, v48
	v_lshlrev_b64 v[54:55], 12, v[48:49]
	v_lshlrev_b64 v[58:59], 12, v[58:59]
	v_lshl_add_u64 v[56:57], s[2:3], 0, v[54:55]
	v_cmp_gt_i32_e32 vcc, s6, v48
	v_lshl_add_u64 v[54:55], s[8:9], 0, v[54:55]
	v_lshl_add_u64 v[58:59], s[10:11], 0, v[58:59]
	v_cndmask_b32_e32 v55, v59, v55, vcc
	v_cndmask_b32_e32 v54, v58, v54, vcc
	v_cndmask_b32_e64 v49, v52, 0, vcc
	v_lshl_add_u64 v[54:55], v[54:55], 0, s[0:1]
	v_add_u32_e32 v49, s4, v49
	v_lshl_add_u64 v[50:51], v[56:57], 0, v[148:149]
	v_cndmask_b32_e64 v54, v56, v54, s[36:37]
	v_mul_lo_u32 v56, v49, s24
	v_cndmask_b32_e64 v55, v57, v55, s[36:37]
	v_ashrrev_i32_e32 v57, 31, v56
	v_lshl_add_u64 v[56:57], v[56:57], 2, s[82:83]
	v_lshl_add_u64 v[56:57], v[56:57], 0, s[0:1]
	v_lshl_add_u64 v[56:57], v[56:57], 0, v[148:149]
	v_lshl_add_u64 v[56:57], v[56:57], 0, v[160:161]
	v_lshl_add_u64 v[58:59], v[56:57], 0, s[14:15]
	v_lshl_add_u64 v[54:55], v[54:55], 0, v[148:149]
	v_add_co_u32_e32 v56, vcc, s12, v56
	v_lshl_add_u64 v[54:55], v[54:55], 0, v[160:161]
	s_nop 0
	v_addc_co_u32_e32 v57, vcc, 0, v57, vcc
	global_load_dword v112, v[54:55], off
	global_load_dword v116, v[56:57], off
	v_lshl_add_u64 v[50:51], v[50:51], 0, v[160:161]
	global_load_dword v113, v[54:55], off offset:64
	global_load_dword v117, v[58:59], off offset:64
	global_load_dword v114, v[54:55], off offset:128
	global_load_dword v118, v[58:59], off offset:128
	global_load_dword v115, v[54:55], off offset:192
	global_load_dword v119, v[58:59], off offset:192
	v_mov_b32_e32 v120, v44
	v_mov_b32_e32 v121, v40
	v_mov_b32_e32 v122, v36
	v_mov_b32_e32 v123, v32
	v_mov_b64_e32 v[124:125], v[50:51]
	s_waitcnt vmcnt(12)
	v_fmac_f32_e32 v126, v134, v130
	v_fmac_f32_e32 v127, v135, v131
	v_fmac_f32_e32 v128, v136, v132
	v_fmac_f32_e32 v129, v137, v133
	global_store_dword v[138:139], v126, off
	global_store_dword v[138:139], v127, off offset:64
	global_store_dword v[138:139], v128, off offset:128
	global_store_dword v[138:139], v129, off offset:192
	v_or_b32_e32 v50, 1, v48
	v_ashrrev_i32_e32 v51, 31, v50
	v_lshlrev_b64 v[54:55], 12, v[50:51]
	v_lshl_add_u64 v[56:57], s[2:3], 0, v[54:55]
	v_cmp_gt_i32_e32 vcc, s6, v50
	v_lshl_add_u64 v[50:51], s[8:9], 0, v[54:55]
	v_add_u32_e32 v54, 0xfffff001, v48
	v_mov_b32_e32 v55, v149
	v_lshlrev_b64 v[54:55], 12, v[54:55]
	v_cndmask_b32_e64 v32, v52, 0, vcc
	v_lshl_add_u64 v[54:55], s[10:11], 0, v[54:55]
	v_add_u32_e32 v32, s4, v32
	v_cndmask_b32_e32 v50, v54, v50, vcc
	v_mul_lo_u32 v54, v32, s24
	v_cndmask_b32_e32 v51, v55, v51, vcc
	v_ashrrev_i32_e32 v55, 31, v54
	v_lshl_add_u64 v[54:55], v[54:55], 2, s[82:83]
	v_lshl_add_u64 v[54:55], v[54:55], 0, s[0:1]
	v_lshl_add_u64 v[50:51], v[50:51], 0, s[0:1]
	v_lshl_add_u64 v[54:55], v[54:55], 0, v[148:149]
	v_cndmask_b32_e64 v51, v57, v51, s[36:37]
	v_cndmask_b32_e64 v50, v56, v50, s[36:37]
	v_lshl_add_u64 v[54:55], v[54:55], 0, v[160:161]
	v_lshl_add_u64 v[58:59], v[56:57], 0, v[148:149]
	v_lshl_add_u64 v[56:57], v[54:55], 0, s[14:15]
	v_lshl_add_u64 v[50:51], v[50:51], 0, v[148:149]
	v_add_co_u32_e32 v54, vcc, s12, v54
	v_lshl_add_u64 v[50:51], v[50:51], 0, v[160:161]
	s_nop 0
	v_addc_co_u32_e32 v55, vcc, 0, v55, vcc
	global_load_dword v126, v[50:51], off
	global_load_dword v130, v[54:55], off
	v_lshl_add_u64 v[58:59], v[58:59], 0, v[160:161]
	global_load_dword v127, v[50:51], off offset:64
	global_load_dword v131, v[56:57], off offset:64
	global_load_dword v128, v[50:51], off offset:128
	global_load_dword v132, v[56:57], off offset:128
	global_load_dword v129, v[50:51], off offset:192
	global_load_dword v133, v[56:57], off offset:192
	v_mov_b32_e32 v134, v45
	v_mov_b32_e32 v135, v41
	v_mov_b32_e32 v136, v37
	v_mov_b32_e32 v137, v33
	v_mov_b64_e32 v[138:139], v[58:59]
	s_waitcnt vmcnt(12)
	v_fmac_f32_e32 v112, v120, v116
	v_fmac_f32_e32 v113, v121, v117
	v_fmac_f32_e32 v114, v122, v118
	v_fmac_f32_e32 v115, v123, v119
	global_store_dword v[124:125], v112, off
	global_store_dword v[124:125], v113, off offset:64
	global_store_dword v[124:125], v114, off offset:128
	global_store_dword v[124:125], v115, off offset:192
	v_or_b32_e32 v32, 2, v48
	v_ashrrev_i32_e32 v33, 31, v32
	v_lshlrev_b64 v[36:37], 12, v[32:33]
	v_lshl_add_u64 v[40:41], s[2:3], 0, v[36:37]
	v_cmp_gt_i32_e32 vcc, s6, v32
	v_lshl_add_u64 v[32:33], s[8:9], 0, v[36:37]
	v_add_u32_e32 v36, 0xfffff002, v48
	v_mov_b32_e32 v37, v149
	v_lshlrev_b64 v[36:37], 12, v[36:37]
	v_lshl_add_u64 v[36:37], s[10:11], 0, v[36:37]
	v_cndmask_b32_e32 v32, v36, v32, vcc
	v_cndmask_b32_e64 v36, v52, 0, vcc
	v_add_u32_e32 v36, s4, v36
	v_mul_lo_u32 v36, v36, s24
	v_cndmask_b32_e32 v33, v37, v33, vcc
	v_ashrrev_i32_e32 v37, 31, v36
	v_lshl_add_u64 v[36:37], v[36:37], 2, s[82:83]
	v_lshl_add_u64 v[36:37], v[36:37], 0, s[0:1]
	v_lshl_add_u64 v[32:33], v[32:33], 0, s[0:1]
	v_lshl_add_u64 v[36:37], v[36:37], 0, v[148:149]
	v_cndmask_b32_e64 v33, v41, v33, s[36:37]
	v_cndmask_b32_e64 v32, v40, v32, s[36:37]
	v_lshl_add_u64 v[36:37], v[36:37], 0, v[160:161]
	v_lshl_add_u64 v[44:45], v[40:41], 0, v[148:149]
	v_lshl_add_u64 v[40:41], v[36:37], 0, s[14:15]
	v_lshl_add_u64 v[32:33], v[32:33], 0, v[148:149]
	v_add_co_u32_e32 v36, vcc, s12, v36
	v_lshl_add_u64 v[32:33], v[32:33], 0, v[160:161]
	s_nop 0
	v_addc_co_u32_e32 v37, vcc, 0, v37, vcc
	global_load_dword v112, v[32:33], off
	v_lshl_add_u64 v[44:45], v[44:45], 0, v[160:161]
	global_load_dword v116, v[36:37], off
	global_load_dword v113, v[32:33], off offset:64
	global_load_dword v117, v[40:41], off offset:64
	global_load_dword v114, v[32:33], off offset:128
	global_load_dword v118, v[40:41], off offset:128
	global_load_dword v115, v[32:33], off offset:192
	global_load_dword v119, v[40:41], off offset:192
	v_mov_b32_e32 v120, v46
	v_mov_b32_e32 v121, v42
	v_mov_b32_e32 v122, v38
	v_mov_b32_e32 v123, v34
	v_mov_b64_e32 v[124:125], v[44:45]
	s_waitcnt vmcnt(12)
	v_fmac_f32_e32 v126, v134, v130
	v_fmac_f32_e32 v127, v135, v131
	v_fmac_f32_e32 v128, v136, v132
	v_fmac_f32_e32 v129, v137, v133
	global_store_dword v[138:139], v126, off
	global_store_dword v[138:139], v127, off offset:64
	global_store_dword v[138:139], v128, off offset:128
	global_store_dword v[138:139], v129, off offset:192
	v_or_b32_e32 v32, 3, v48
	v_ashrrev_i32_e32 v33, 31, v32
	v_lshlrev_b64 v[36:37], 12, v[32:33]
	v_lshl_add_u64 v[40:41], s[2:3], 0, v[36:37]
	v_cmp_gt_i32_e32 vcc, s6, v32
	v_lshl_add_u64 v[32:33], s[8:9], 0, v[36:37]
	v_add_u32_e32 v36, 0xfffff003, v48
	v_mov_b32_e32 v37, v149
	v_lshlrev_b64 v[36:37], 12, v[36:37]
	v_cndmask_b32_e64 v34, v52, 0, vcc
	v_lshl_add_u64 v[36:37], s[10:11], 0, v[36:37]
	v_add_u32_e32 v34, s4, v34
	v_cndmask_b32_e32 v32, v36, v32, vcc
	v_mul_lo_u32 v36, v34, s24
	v_cndmask_b32_e32 v33, v37, v33, vcc
	v_ashrrev_i32_e32 v37, 31, v36
	v_lshl_add_u64 v[36:37], v[36:37], 2, s[82:83]
	v_lshl_add_u64 v[36:37], v[36:37], 0, s[0:1]
	v_lshl_add_u64 v[32:33], v[32:33], 0, s[0:1]
	v_lshl_add_u64 v[36:37], v[36:37], 0, v[148:149]
	v_cndmask_b32_e64 v33, v41, v33, s[36:37]
	v_cndmask_b32_e64 v32, v40, v32, s[36:37]
	v_lshl_add_u64 v[36:37], v[36:37], 0, v[160:161]
	v_lshl_add_u64 v[44:45], v[40:41], 0, v[148:149]
	v_lshl_add_u64 v[40:41], v[36:37], 0, s[14:15]
	v_lshl_add_u64 v[32:33], v[32:33], 0, v[148:149]
	v_add_co_u32_e32 v36, vcc, s12, v36
	v_lshl_add_u64 v[32:33], v[32:33], 0, v[160:161]
	s_nop 0
	v_addc_co_u32_e32 v37, vcc, 0, v37, vcc
	global_load_dword v126, v[32:33], off
	v_lshl_add_u64 v[44:45], v[44:45], 0, v[160:161]
	global_load_dword v130, v[36:37], off
	global_load_dword v127, v[32:33], off offset:64
	global_load_dword v131, v[40:41], off offset:64
	global_load_dword v128, v[32:33], off offset:128
	global_load_dword v132, v[40:41], off offset:128
	global_load_dword v129, v[32:33], off offset:192
	global_load_dword v133, v[40:41], off offset:192
	v_mov_b32_e32 v134, v47
	v_mov_b32_e32 v135, v43
	v_mov_b32_e32 v136, v39
	v_mov_b32_e32 v137, v35
	v_mov_b64_e32 v[138:139], v[44:45]
	s_waitcnt vmcnt(12)
	v_fmac_f32_e32 v112, v120, v116
	v_fmac_f32_e32 v113, v121, v117
	v_fmac_f32_e32 v114, v122, v118
	v_fmac_f32_e32 v115, v123, v119
	global_store_dword v[124:125], v112, off
	global_store_dword v[124:125], v113, off offset:64
	global_store_dword v[124:125], v114, off offset:128
	global_store_dword v[124:125], v115, off offset:192
	v_mov_b32_e32 v43, v149
	v_add_u32_e32 v33, 0xfffff040, v98
	v_add_u32_e32 v32, v98, v170
	v_lshrrev_b32_e32 v33, 12, v33
	v_add_u32_e32 v36, 1, v33
	v_ashrrev_i32_e32 v33, 31, v32
	v_add_u32_e32 v42, 0xfffff000, v32
	v_lshlrev_b64 v[38:39], 12, v[32:33]
	v_lshlrev_b64 v[42:43], 12, v[42:43]
	v_lshl_add_u64 v[40:41], s[2:3], 0, v[38:39]
	v_cmp_gt_i32_e32 vcc, s6, v32
	v_lshl_add_u64 v[38:39], s[8:9], 0, v[38:39]
	v_lshl_add_u64 v[42:43], s[10:11], 0, v[42:43]
	v_cndmask_b32_e32 v39, v43, v39, vcc
	v_cndmask_b32_e32 v38, v42, v38, vcc
	v_cndmask_b32_e64 v33, v36, 0, vcc
	v_lshl_add_u64 v[38:39], v[38:39], 0, s[0:1]
	v_add_u32_e32 v33, s4, v33
	v_lshl_add_u64 v[34:35], v[40:41], 0, v[148:149]
	v_cndmask_b32_e64 v38, v40, v38, s[36:37]
	v_mul_lo_u32 v40, v33, s24
	v_cndmask_b32_e64 v39, v41, v39, s[36:37]
	v_ashrrev_i32_e32 v41, 31, v40
	v_lshl_add_u64 v[40:41], v[40:41], 2, s[82:83]
	v_lshl_add_u64 v[40:41], v[40:41], 0, s[0:1]
	v_lshl_add_u64 v[40:41], v[40:41], 0, v[148:149]
	v_lshl_add_u64 v[40:41], v[40:41], 0, v[160:161]
	v_lshl_add_u64 v[42:43], v[40:41], 0, s[14:15]
	v_lshl_add_u64 v[38:39], v[38:39], 0, v[148:149]
	v_add_co_u32_e32 v40, vcc, s12, v40
	v_lshl_add_u64 v[38:39], v[38:39], 0, v[160:161]
	s_nop 0
	v_addc_co_u32_e32 v41, vcc, 0, v41, vcc
	global_load_dword v112, v[38:39], off
	global_load_dword v116, v[40:41], off
	v_lshl_add_u64 v[34:35], v[34:35], 0, v[160:161]
	global_load_dword v113, v[38:39], off offset:64
	global_load_dword v117, v[42:43], off offset:64
	global_load_dword v114, v[38:39], off offset:128
	global_load_dword v118, v[42:43], off offset:128
	global_load_dword v115, v[38:39], off offset:192
	global_load_dword v119, v[42:43], off offset:192
	v_mov_b32_e32 v120, v28
	v_mov_b32_e32 v121, v24
	v_mov_b32_e32 v122, v20
	v_mov_b32_e32 v123, v16
	v_mov_b64_e32 v[124:125], v[34:35]
	s_waitcnt vmcnt(12)
	v_fmac_f32_e32 v126, v134, v130
	v_fmac_f32_e32 v127, v135, v131
	v_fmac_f32_e32 v128, v136, v132
	v_fmac_f32_e32 v129, v137, v133
	global_store_dword v[138:139], v126, off
	global_store_dword v[138:139], v127, off offset:64
	global_store_dword v[138:139], v128, off offset:128
	global_store_dword v[138:139], v129, off offset:192
	v_or_b32_e32 v34, 1, v32
	v_ashrrev_i32_e32 v35, 31, v34
	v_lshlrev_b64 v[38:39], 12, v[34:35]
	v_lshl_add_u64 v[40:41], s[2:3], 0, v[38:39]
	v_cmp_gt_i32_e32 vcc, s6, v34
	v_lshl_add_u64 v[34:35], s[8:9], 0, v[38:39]
	v_add_u32_e32 v38, 0xfffff001, v32
	v_mov_b32_e32 v39, v149
	v_lshlrev_b64 v[38:39], 12, v[38:39]
	v_cndmask_b32_e64 v16, v36, 0, vcc
	v_lshl_add_u64 v[38:39], s[10:11], 0, v[38:39]
	v_add_u32_e32 v16, s4, v16
	v_cndmask_b32_e32 v34, v38, v34, vcc
	v_mul_lo_u32 v38, v16, s24
	v_cndmask_b32_e32 v35, v39, v35, vcc
	v_ashrrev_i32_e32 v39, 31, v38
	v_lshl_add_u64 v[38:39], v[38:39], 2, s[82:83]
	v_lshl_add_u64 v[38:39], v[38:39], 0, s[0:1]
	v_lshl_add_u64 v[34:35], v[34:35], 0, s[0:1]
	v_lshl_add_u64 v[38:39], v[38:39], 0, v[148:149]
	v_cndmask_b32_e64 v35, v41, v35, s[36:37]
	v_cndmask_b32_e64 v34, v40, v34, s[36:37]
	v_lshl_add_u64 v[38:39], v[38:39], 0, v[160:161]
	v_lshl_add_u64 v[42:43], v[40:41], 0, v[148:149]
	v_lshl_add_u64 v[40:41], v[38:39], 0, s[14:15]
	v_lshl_add_u64 v[34:35], v[34:35], 0, v[148:149]
	v_add_co_u32_e32 v38, vcc, s12, v38
	v_lshl_add_u64 v[34:35], v[34:35], 0, v[160:161]
	s_nop 0
	v_addc_co_u32_e32 v39, vcc, 0, v39, vcc
	global_load_dword v126, v[34:35], off
	global_load_dword v130, v[38:39], off
	v_lshl_add_u64 v[42:43], v[42:43], 0, v[160:161]
	global_load_dword v127, v[34:35], off offset:64
	global_load_dword v131, v[40:41], off offset:64
	global_load_dword v128, v[34:35], off offset:128
	global_load_dword v132, v[40:41], off offset:128
	global_load_dword v129, v[34:35], off offset:192
	global_load_dword v133, v[40:41], off offset:192
	v_mov_b32_e32 v134, v29
	v_mov_b32_e32 v135, v25
	v_mov_b32_e32 v136, v21
	v_mov_b32_e32 v137, v17
	v_mov_b64_e32 v[138:139], v[42:43]
	s_waitcnt vmcnt(12)
	v_fmac_f32_e32 v112, v120, v116
	v_fmac_f32_e32 v113, v121, v117
	v_fmac_f32_e32 v114, v122, v118
	v_fmac_f32_e32 v115, v123, v119
	global_store_dword v[124:125], v112, off
	global_store_dword v[124:125], v113, off offset:64
	global_store_dword v[124:125], v114, off offset:128
	global_store_dword v[124:125], v115, off offset:192
	v_or_b32_e32 v16, 2, v32
	v_ashrrev_i32_e32 v17, 31, v16
	v_lshlrev_b64 v[20:21], 12, v[16:17]
	v_lshl_add_u64 v[24:25], s[2:3], 0, v[20:21]
	v_cmp_gt_i32_e32 vcc, s6, v16
	v_lshl_add_u64 v[16:17], s[8:9], 0, v[20:21]
	v_add_u32_e32 v20, 0xfffff002, v32
	v_mov_b32_e32 v21, v149
	v_lshlrev_b64 v[20:21], 12, v[20:21]
	v_lshl_add_u64 v[20:21], s[10:11], 0, v[20:21]
	v_cndmask_b32_e32 v16, v20, v16, vcc
	v_cndmask_b32_e64 v20, v36, 0, vcc
	v_add_u32_e32 v20, s4, v20
	v_mul_lo_u32 v20, v20, s24
	v_cndmask_b32_e32 v17, v21, v17, vcc
	v_ashrrev_i32_e32 v21, 31, v20
	v_lshl_add_u64 v[20:21], v[20:21], 2, s[82:83]
	v_lshl_add_u64 v[20:21], v[20:21], 0, s[0:1]
	v_lshl_add_u64 v[16:17], v[16:17], 0, s[0:1]
	v_lshl_add_u64 v[20:21], v[20:21], 0, v[148:149]
	v_cndmask_b32_e64 v17, v25, v17, s[36:37]
	v_cndmask_b32_e64 v16, v24, v16, s[36:37]
	v_lshl_add_u64 v[20:21], v[20:21], 0, v[160:161]
	v_lshl_add_u64 v[28:29], v[24:25], 0, v[148:149]
	v_lshl_add_u64 v[24:25], v[20:21], 0, s[14:15]
	v_lshl_add_u64 v[16:17], v[16:17], 0, v[148:149]
	v_add_co_u32_e32 v20, vcc, s12, v20
	v_lshl_add_u64 v[16:17], v[16:17], 0, v[160:161]
	s_nop 0
	v_addc_co_u32_e32 v21, vcc, 0, v21, vcc
	global_load_dword v112, v[16:17], off
	v_lshl_add_u64 v[28:29], v[28:29], 0, v[160:161]
	global_load_dword v116, v[20:21], off
	global_load_dword v113, v[16:17], off offset:64
	global_load_dword v117, v[24:25], off offset:64
	global_load_dword v114, v[16:17], off offset:128
	global_load_dword v118, v[24:25], off offset:128
	global_load_dword v115, v[16:17], off offset:192
	global_load_dword v119, v[24:25], off offset:192
	v_mov_b32_e32 v120, v30
	v_mov_b32_e32 v121, v26
	v_mov_b32_e32 v122, v22
	v_mov_b32_e32 v123, v18
	v_mov_b64_e32 v[124:125], v[28:29]
	s_waitcnt vmcnt(12)
	v_fmac_f32_e32 v126, v134, v130
	v_fmac_f32_e32 v127, v135, v131
	v_fmac_f32_e32 v128, v136, v132
	v_fmac_f32_e32 v129, v137, v133
	global_store_dword v[138:139], v126, off
	global_store_dword v[138:139], v127, off offset:64
	global_store_dword v[138:139], v128, off offset:128
	global_store_dword v[138:139], v129, off offset:192
	v_or_b32_e32 v16, 3, v32
	v_ashrrev_i32_e32 v17, 31, v16
	v_lshlrev_b64 v[20:21], 12, v[16:17]
	v_lshl_add_u64 v[24:25], s[2:3], 0, v[20:21]
	v_cmp_gt_i32_e32 vcc, s6, v16
	v_lshl_add_u64 v[16:17], s[8:9], 0, v[20:21]
	v_add_u32_e32 v20, 0xfffff003, v32
	v_mov_b32_e32 v21, v149
	v_lshlrev_b64 v[20:21], 12, v[20:21]
	v_cndmask_b32_e64 v18, v36, 0, vcc
	v_lshl_add_u64 v[20:21], s[10:11], 0, v[20:21]
	v_add_u32_e32 v18, s4, v18
	v_cndmask_b32_e32 v16, v20, v16, vcc
	v_mul_lo_u32 v20, v18, s24
	v_cndmask_b32_e32 v17, v21, v17, vcc
	v_ashrrev_i32_e32 v21, 31, v20
	v_lshl_add_u64 v[20:21], v[20:21], 2, s[82:83]
	v_lshl_add_u64 v[20:21], v[20:21], 0, s[0:1]
	v_lshl_add_u64 v[16:17], v[16:17], 0, s[0:1]
	v_lshl_add_u64 v[20:21], v[20:21], 0, v[148:149]
	v_cndmask_b32_e64 v17, v25, v17, s[36:37]
	v_cndmask_b32_e64 v16, v24, v16, s[36:37]
	v_lshl_add_u64 v[20:21], v[20:21], 0, v[160:161]
	v_lshl_add_u64 v[28:29], v[24:25], 0, v[148:149]
	v_lshl_add_u64 v[24:25], v[20:21], 0, s[14:15]
	v_lshl_add_u64 v[16:17], v[16:17], 0, v[148:149]
	v_add_co_u32_e32 v20, vcc, s12, v20
	v_lshl_add_u64 v[16:17], v[16:17], 0, v[160:161]
	s_nop 0
	v_addc_co_u32_e32 v21, vcc, 0, v21, vcc
	global_load_dword v126, v[16:17], off
	v_lshl_add_u64 v[28:29], v[28:29], 0, v[160:161]
	global_load_dword v130, v[20:21], off
	global_load_dword v127, v[16:17], off offset:64
	global_load_dword v131, v[24:25], off offset:64
	global_load_dword v128, v[16:17], off offset:128
	global_load_dword v132, v[24:25], off offset:128
	global_load_dword v129, v[16:17], off offset:192
	global_load_dword v133, v[24:25], off offset:192
	v_mov_b32_e32 v134, v31
	v_mov_b32_e32 v135, v27
	v_mov_b32_e32 v136, v23
	v_mov_b32_e32 v137, v19
	v_mov_b64_e32 v[138:139], v[28:29]
	s_waitcnt vmcnt(12)
	v_fmac_f32_e32 v112, v120, v116
	v_fmac_f32_e32 v113, v121, v117
	v_fmac_f32_e32 v114, v122, v118
	v_fmac_f32_e32 v115, v123, v119
	global_store_dword v[124:125], v112, off
	global_store_dword v[124:125], v113, off offset:64
	global_store_dword v[124:125], v114, off offset:128
	global_store_dword v[124:125], v115, off offset:192
	v_mov_b32_e32 v27, v149
	v_add_u32_e32 v17, 0xfffff050, v98
	v_add_u32_e32 v16, v98, v171
	v_lshrrev_b32_e32 v17, 12, v17
	v_add_u32_e32 v20, 1, v17
	v_ashrrev_i32_e32 v17, 31, v16
	v_add_u32_e32 v26, 0xfffff000, v16
	v_lshlrev_b64 v[22:23], 12, v[16:17]
	v_lshlrev_b64 v[26:27], 12, v[26:27]
	v_lshl_add_u64 v[24:25], s[2:3], 0, v[22:23]
	v_cmp_gt_i32_e32 vcc, s6, v16
	v_lshl_add_u64 v[22:23], s[8:9], 0, v[22:23]
	v_lshl_add_u64 v[26:27], s[10:11], 0, v[26:27]
	v_cndmask_b32_e32 v23, v27, v23, vcc
	v_cndmask_b32_e32 v22, v26, v22, vcc
	v_cndmask_b32_e64 v17, v20, 0, vcc
	v_lshl_add_u64 v[22:23], v[22:23], 0, s[0:1]
	v_add_u32_e32 v17, s4, v17
	v_lshl_add_u64 v[18:19], v[24:25], 0, v[148:149]
	v_cndmask_b32_e64 v22, v24, v22, s[36:37]
	v_mul_lo_u32 v24, v17, s24
	v_cndmask_b32_e64 v23, v25, v23, s[36:37]
	v_ashrrev_i32_e32 v25, 31, v24
	v_lshl_add_u64 v[24:25], v[24:25], 2, s[82:83]
	v_lshl_add_u64 v[24:25], v[24:25], 0, s[0:1]
	v_lshl_add_u64 v[24:25], v[24:25], 0, v[148:149]
	v_lshl_add_u64 v[24:25], v[24:25], 0, v[160:161]
	v_lshl_add_u64 v[26:27], v[24:25], 0, s[14:15]
	v_lshl_add_u64 v[22:23], v[22:23], 0, v[148:149]
	v_add_co_u32_e32 v24, vcc, s12, v24
	v_lshl_add_u64 v[22:23], v[22:23], 0, v[160:161]
	s_nop 0
	v_addc_co_u32_e32 v25, vcc, 0, v25, vcc
	global_load_dword v112, v[22:23], off
	global_load_dword v116, v[24:25], off
	v_lshl_add_u64 v[18:19], v[18:19], 0, v[160:161]
	global_load_dword v113, v[22:23], off offset:64
	global_load_dword v117, v[26:27], off offset:64
	global_load_dword v114, v[22:23], off offset:128
	global_load_dword v118, v[26:27], off offset:128
	global_load_dword v115, v[22:23], off offset:192
	global_load_dword v119, v[26:27], off offset:192
	v_mov_b32_e32 v120, v12
	v_mov_b32_e32 v121, v8
	v_mov_b32_e32 v122, v4
	v_mov_b32_e32 v123, v0
	v_mov_b64_e32 v[124:125], v[18:19]
	s_waitcnt vmcnt(12)
	v_fmac_f32_e32 v126, v134, v130
	v_fmac_f32_e32 v127, v135, v131
	v_fmac_f32_e32 v128, v136, v132
	v_fmac_f32_e32 v129, v137, v133
	global_store_dword v[138:139], v126, off
	global_store_dword v[138:139], v127, off offset:64
	global_store_dword v[138:139], v128, off offset:128
	global_store_dword v[138:139], v129, off offset:192
	v_or_b32_e32 v18, 1, v16
	v_ashrrev_i32_e32 v19, 31, v18
	v_lshlrev_b64 v[22:23], 12, v[18:19]
	v_lshl_add_u64 v[24:25], s[2:3], 0, v[22:23]
	v_cmp_gt_i32_e32 vcc, s6, v18
	v_lshl_add_u64 v[18:19], s[8:9], 0, v[22:23]
	v_add_u32_e32 v22, 0xfffff001, v16
	v_mov_b32_e32 v23, v149
	v_lshlrev_b64 v[22:23], 12, v[22:23]
	v_cndmask_b32_e64 v0, v20, 0, vcc
	v_lshl_add_u64 v[22:23], s[10:11], 0, v[22:23]
	v_add_u32_e32 v0, s4, v0
	v_cndmask_b32_e32 v18, v22, v18, vcc
	v_mul_lo_u32 v22, v0, s24
	v_cndmask_b32_e32 v19, v23, v19, vcc
	v_ashrrev_i32_e32 v23, 31, v22
	v_lshl_add_u64 v[22:23], v[22:23], 2, s[82:83]
	v_lshl_add_u64 v[22:23], v[22:23], 0, s[0:1]
	v_lshl_add_u64 v[18:19], v[18:19], 0, s[0:1]
	v_lshl_add_u64 v[22:23], v[22:23], 0, v[148:149]
	v_cndmask_b32_e64 v19, v25, v19, s[36:37]
	v_cndmask_b32_e64 v18, v24, v18, s[36:37]
	v_lshl_add_u64 v[22:23], v[22:23], 0, v[160:161]
	v_lshl_add_u64 v[26:27], v[24:25], 0, v[148:149]
	v_lshl_add_u64 v[24:25], v[22:23], 0, s[14:15]
	v_lshl_add_u64 v[18:19], v[18:19], 0, v[148:149]
	v_add_co_u32_e32 v22, vcc, s12, v22
	v_lshl_add_u64 v[18:19], v[18:19], 0, v[160:161]
	s_nop 0
	v_addc_co_u32_e32 v23, vcc, 0, v23, vcc
	global_load_dword v126, v[18:19], off
	global_load_dword v130, v[22:23], off
	v_lshl_add_u64 v[26:27], v[26:27], 0, v[160:161]
	global_load_dword v127, v[18:19], off offset:64
	global_load_dword v131, v[24:25], off offset:64
	global_load_dword v128, v[18:19], off offset:128
	global_load_dword v132, v[24:25], off offset:128
	global_load_dword v129, v[18:19], off offset:192
	global_load_dword v133, v[24:25], off offset:192
	v_mov_b32_e32 v134, v13
	v_mov_b32_e32 v135, v9
	v_mov_b32_e32 v136, v5
	v_mov_b32_e32 v137, v1
	v_mov_b64_e32 v[138:139], v[26:27]
	s_waitcnt vmcnt(12)
	v_fmac_f32_e32 v112, v120, v116
	v_fmac_f32_e32 v113, v121, v117
	v_fmac_f32_e32 v114, v122, v118
	v_fmac_f32_e32 v115, v123, v119
	global_store_dword v[124:125], v112, off
	global_store_dword v[124:125], v113, off offset:64
	global_store_dword v[124:125], v114, off offset:128
	global_store_dword v[124:125], v115, off offset:192
	v_or_b32_e32 v0, 2, v16
	v_ashrrev_i32_e32 v1, 31, v0
	v_lshlrev_b64 v[4:5], 12, v[0:1]
	v_lshl_add_u64 v[8:9], s[2:3], 0, v[4:5]
	v_cmp_gt_i32_e32 vcc, s6, v0
	v_lshl_add_u64 v[0:1], s[8:9], 0, v[4:5]
	v_add_u32_e32 v4, 0xfffff002, v16
	v_mov_b32_e32 v5, v149
	v_lshlrev_b64 v[4:5], 12, v[4:5]
	v_lshl_add_u64 v[4:5], s[10:11], 0, v[4:5]
	v_cndmask_b32_e32 v0, v4, v0, vcc
	v_cndmask_b32_e64 v4, v20, 0, vcc
	v_add_u32_e32 v4, s4, v4
	v_mul_lo_u32 v4, v4, s24
	v_cndmask_b32_e32 v1, v5, v1, vcc
	v_ashrrev_i32_e32 v5, 31, v4
	v_lshl_add_u64 v[4:5], v[4:5], 2, s[82:83]
	v_lshl_add_u64 v[4:5], v[4:5], 0, s[0:1]
	v_lshl_add_u64 v[0:1], v[0:1], 0, s[0:1]
	v_lshl_add_u64 v[4:5], v[4:5], 0, v[148:149]
	v_cndmask_b32_e64 v1, v9, v1, s[36:37]
	v_cndmask_b32_e64 v0, v8, v0, s[36:37]
	v_lshl_add_u64 v[4:5], v[4:5], 0, v[160:161]
	v_lshl_add_u64 v[12:13], v[8:9], 0, v[148:149]
	v_lshl_add_u64 v[8:9], v[4:5], 0, s[14:15]
	v_lshl_add_u64 v[0:1], v[0:1], 0, v[148:149]
	v_add_co_u32_e32 v4, vcc, s12, v4
	v_lshl_add_u64 v[0:1], v[0:1], 0, v[160:161]
	s_nop 0
	v_addc_co_u32_e32 v5, vcc, 0, v5, vcc
	global_load_dword v112, v[0:1], off
	v_lshl_add_u64 v[12:13], v[12:13], 0, v[160:161]
	global_load_dword v116, v[4:5], off
	global_load_dword v113, v[0:1], off offset:64
	global_load_dword v117, v[8:9], off offset:64
	global_load_dword v114, v[0:1], off offset:128
	global_load_dword v118, v[8:9], off offset:128
	global_load_dword v115, v[0:1], off offset:192
	global_load_dword v119, v[8:9], off offset:192
	v_mov_b32_e32 v120, v14
	v_mov_b32_e32 v121, v10
	v_mov_b32_e32 v122, v6
	v_mov_b32_e32 v123, v2
	v_mov_b64_e32 v[124:125], v[12:13]
	s_waitcnt vmcnt(12)
	v_fmac_f32_e32 v126, v134, v130
	v_fmac_f32_e32 v127, v135, v131
	v_fmac_f32_e32 v128, v136, v132
	v_fmac_f32_e32 v129, v137, v133
	global_store_dword v[138:139], v126, off
	global_store_dword v[138:139], v127, off offset:64
	global_store_dword v[138:139], v128, off offset:128
	global_store_dword v[138:139], v129, off offset:192
	v_or_b32_e32 v0, 3, v16
	v_ashrrev_i32_e32 v1, 31, v0
	v_lshlrev_b64 v[4:5], 12, v[0:1]
	v_lshl_add_u64 v[8:9], s[2:3], 0, v[4:5]
	v_cmp_gt_i32_e32 vcc, s6, v0
	v_lshl_add_u64 v[0:1], s[8:9], 0, v[4:5]
	v_add_u32_e32 v4, 0xfffff003, v16
	v_mov_b32_e32 v5, v149
	v_lshlrev_b64 v[4:5], 12, v[4:5]
	v_cndmask_b32_e64 v2, v20, 0, vcc
	v_lshl_add_u64 v[4:5], s[10:11], 0, v[4:5]
	v_add_u32_e32 v2, s4, v2
	v_cndmask_b32_e32 v0, v4, v0, vcc
	v_mul_lo_u32 v4, v2, s24
	v_cndmask_b32_e32 v1, v5, v1, vcc
	v_ashrrev_i32_e32 v5, 31, v4
	v_lshl_add_u64 v[4:5], v[4:5], 2, s[82:83]
	v_lshl_add_u64 v[4:5], v[4:5], 0, s[0:1]
	v_lshl_add_u64 v[0:1], v[0:1], 0, s[0:1]
	v_lshl_add_u64 v[4:5], v[4:5], 0, v[148:149]
	v_cndmask_b32_e64 v1, v9, v1, s[36:37]
	v_cndmask_b32_e64 v0, v8, v0, s[36:37]
	v_lshl_add_u64 v[4:5], v[4:5], 0, v[160:161]
	v_lshl_add_u64 v[12:13], v[8:9], 0, v[148:149]
	v_lshl_add_u64 v[8:9], v[4:5], 0, s[14:15]
	v_lshl_add_u64 v[0:1], v[0:1], 0, v[148:149]
	v_add_co_u32_e32 v4, vcc, s12, v4
	v_lshl_add_u64 v[0:1], v[0:1], 0, v[160:161]
	s_nop 0
	v_addc_co_u32_e32 v5, vcc, 0, v5, vcc
	global_load_dword v126, v[0:1], off
	v_lshl_add_u64 v[12:13], v[12:13], 0, v[160:161]
	global_load_dword v130, v[4:5], off
	global_load_dword v127, v[0:1], off offset:64
	global_load_dword v131, v[8:9], off offset:64
	global_load_dword v128, v[0:1], off offset:128
	global_load_dword v132, v[8:9], off offset:128
	global_load_dword v129, v[0:1], off offset:192
	global_load_dword v133, v[8:9], off offset:192
	v_mov_b32_e32 v134, v15
	v_mov_b32_e32 v135, v11
	v_mov_b32_e32 v136, v7
	v_mov_b32_e32 v137, v3
	v_mov_b64_e32 v[138:139], v[12:13]
	s_waitcnt vmcnt(12)
	v_fmac_f32_e32 v112, v120, v116
	v_fmac_f32_e32 v113, v121, v117
	v_fmac_f32_e32 v114, v122, v118
	v_fmac_f32_e32 v115, v123, v119
	global_store_dword v[124:125], v112, off
	global_store_dword v[124:125], v113, off offset:64
	global_store_dword v[124:125], v114, off offset:128
	global_store_dword v[124:125], v115, off offset:192
	s_waitcnt vmcnt(4)
	v_fmac_f32_e32 v126, v134, v130
	v_fmac_f32_e32 v127, v135, v131
	v_fmac_f32_e32 v128, v136, v132
	v_fmac_f32_e32 v129, v137, v133
	global_store_dword v[138:139], v126, off
	global_store_dword v[138:139], v127, off offset:64
	global_store_dword v[138:139], v128, off offset:128
	global_store_dword v[138:139], v129, off offset:192
	s_cbranch_scc0 .LBB0_1136
